# barrier release spin without the s_sleep between polls
# baseline (speedup 1.0000x reference)
.Lxb_spin_0:
	global_load_dword v5, v6, s[14:15] sc1
	s_add_u32 s16, s16, 1
	s_waitcnt vmcnt(0)
	v_cmp_ge_u32_e32 vcc, v5, v4
	s_cbranch_vccnz .Lxb_done_0
	s_cmp_lt_u32 s16, 0x200000
	s_cbranch_scc0 .Lxb_done_0
	s_branch .Lxb_spin_0
